# speedup vs baseline: 1.0180x; 1.0026x over previous
; #define LBAR() asm volatile("s_waitcnt lgkmcnt(0)\n\ts_barrier" ::: "memory")
; #define MFMA16(a, b, c) __builtin_amdgcn_mfma_f32_16x16x32_bf16((a), (b), (c), 0, 0, 0)
; #define R2_BLOAD(slot, q) do { _Pragma("unroll") for (int ct = 0; ct < R2_NCT; ++ct) bq[slot][ct] = ((q) < 8) ? *(const bf16x8*)(ST + (ct * 16 + r16) * 264 + (q) * 32 + g4 * 8) : *(const bf16x8*)(VT + (ct * 16 + r16) * 136 + ((q) - 8) * 32 + g4 * 8); } while (0)
; __global__ void __launch_bounds__(512, 2) fwd_megakernel(Params kp_) {
;     ...
;                                 bf16* ST = ST0 + (n & 1) * (R2_NCT * 16 * 264); bf16* STn = ST0 + ((n + 1) & 1) * (R2_NCT * 16 * 264); bf16* VT = VT0 + (n & 1) * (R2_NCT * 16 * 136);
; #pragma unroll
;                                 for (int it = 0; it < R2_NCT / 2; ++it) { const int idx_ = tid + 512 * it, i = idx_ >> 2, c8 = idx_ & 3; const u32x4 w = vreg[it];
; #pragma unroll
;                                     for (int e = 0; e < 4; ++e) { VT[(c8 * 8 + 2 * e) * 136 + i] = (bf16)(w[e] & 0xffffu); VT[(c8 * 8 + 2 * e + 1) * 136 + i] = (bf16)(w[e] >> 16); } }
;                                 LBAR();
;                                 f32x4 acc[R2_NCT];
; #pragma unroll
;                                 for (int ct = 0; ct < R2_NCT; ++ct) acc[ct] = (f32x4){0.f, 0.f, 0.f, 0.f};
;                                 {
;                                     bf16x8 bq[3][R2_NCT];
;     ...
;                                     R2_BLOAD(0, 0); R2_BLOAD(1, 1);
; #pragma unroll
;                                     for (int q = 0; q < 12; ++q) {
;                                         if (q + 2 < 12) R2_BLOAD((q + 2) % 3, q + 2);
;                                         __builtin_amdgcn_sched_barrier(0);
; #pragma unroll
;                                         for (int ct = 0; ct < R2_NCT; ++ct) acc[ct] = MFMA16(bq[q % 3][ct], afr[q], acc[ct]);
;                                         __builtin_amdgcn_sched_barrier(0);
;                                     }
;     ...
;                                 }
;                                 { const size_t rown = (n < 63) ? row0 + 128 : row0; R2_LOAD_A(rown); }
.LBB0_558:
	s_and_b32 s1, s0, 1
	s_mul_i32 s4, s1, 0x2200
	s_add_i32 s11, s4, 0
	s_lshl_b32 s1, s1, 13
	v_lshlrev_b32_e32 v115, 1, v104
	s_add_i32 s1, s11, s1
	v_add3_u32 v131, s11, v115, v103
	v_add3_u32 v115, s11, v103, v115
	s_waitcnt vmcnt(8)
	ds_write_b16 v131, v84 offset:33792
	ds_write_b16_d16_hi v115, v84 offset:34064
	ds_write_b16 v131, v85 offset:34336
	ds_write_b16_d16_hi v115, v85 offset:34608
	ds_write_b16 v131, v86 offset:34880
	ds_write_b16_d16_hi v115, v86 offset:35152
	ds_write_b16 v131, v87 offset:35424
	ds_write_b16_d16_hi v115, v87 offset:35696
	v_add_u32_e32 v115, s1, v196
	s_waitcnt lgkmcnt(0)
	s_barrier
	v_add_u32_e32 v131, v115, v124
	ds_read_b128 v[84:87], v131
	ds_read_b128 v[132:135], v131 offset:8448
	v_add3_u32 v131, s1, v124, v196
	v_add_u32_e32 v115, v115, v125
	ds_read_b128 v[136:139], v131 offset:64
	ds_read_b128 v[140:143], v131 offset:128
	ds_read_b128 v[144:147], v115 offset:64
	ds_read_b128 v[148:151], v115 offset:128
	s_add_i32 s9, s0, 1
	s_and_b32 s10, 1, s9
	s_add_u32 s4, s6, 0x80
	s_addc_u32 s5, s7, 0
	s_cmp_eq_u32 s0, 63
	s_cselect_b32 s0, s6, s4
	s_cselect_b32 s6, 0x1f8000, s8
	s_cselect_b32 s1, s7, s5
	s_cmp_eq_u32 s10, 1
	s_waitcnt lgkmcnt(5)
	v_mfma_f32_16x16x32_bf16 v[84:87], v[84:87], v[60:63], 0
	s_waitcnt lgkmcnt(4)
	v_mfma_f32_16x16x32_bf16 v[60:63], v[132:135], v[60:63], 0
	ds_read_b128 v[132:135], v131 offset:192
	ds_read_b128 v[152:155], v115 offset:192
	s_waitcnt lgkmcnt(5)
	v_mfma_f32_16x16x32_bf16 v[84:87], v[136:139], v[40:43], v[84:87]
	s_waitcnt lgkmcnt(3)
	v_mfma_f32_16x16x32_bf16 v[40:43], v[144:147], v[40:43], v[60:63]
	s_nop 2
	ds_read_b128 v[60:63], v131 offset:256
	ds_read_b128 v[136:139], v115 offset:256
	v_mfma_f32_16x16x32_bf16 v[84:87], v[140:143], v[36:39], v[84:87]
	s_waitcnt lgkmcnt(4)
	v_mfma_f32_16x16x32_bf16 v[36:39], v[148:151], v[36:39], v[40:43]
	s_nop 2
	ds_read_b128 v[40:43], v131 offset:320
	ds_read_b128 v[140:143], v115 offset:320
	s_waitcnt lgkmcnt(5)
	v_mfma_f32_16x16x32_bf16 v[84:87], v[132:135], v[32:35], v[84:87]
	s_waitcnt lgkmcnt(4)
	v_mfma_f32_16x16x32_bf16 v[32:35], v[152:155], v[32:35], v[36:39]
	s_nop 2
	ds_read_b128 v[36:39], v131 offset:384
	ds_read_b128 v[132:135], v115 offset:384
	s_waitcnt lgkmcnt(5)
	v_mfma_f32_16x16x32_bf16 v[60:63], v[60:63], v[28:31], v[84:87]
	s_waitcnt lgkmcnt(4)
	v_mfma_f32_16x16x32_bf16 v[28:31], v[136:139], v[28:31], v[32:35]
	s_nop 2
	ds_read_b128 v[32:35], v131 offset:448
	ds_read_b128 v[84:87], v115 offset:448
	s_waitcnt lgkmcnt(5)
	v_mfma_f32_16x16x32_bf16 v[40:43], v[40:43], v[24:27], v[60:63]
	s_waitcnt lgkmcnt(4)
	v_mfma_f32_16x16x32_bf16 v[24:27], v[140:143], v[24:27], v[28:31]
	v_add3_u32 v115, s11, v126, v196
	v_add_u32_e32 v131, s11, v196
	v_add_u32_e32 v136, v131, v127
	ds_read_b128 v[28:31], v115 offset:33792
	ds_read_b128 v[60:63], v136 offset:33792
	s_waitcnt lgkmcnt(5)
	v_mfma_f32_16x16x32_bf16 v[36:39], v[36:39], v[20:23], v[40:43]
	s_waitcnt lgkmcnt(4)
	v_mfma_f32_16x16x32_bf16 v[20:23], v[132:135], v[20:23], v[24:27]
	s_nop 2
	ds_read_b128 v[24:27], v115 offset:33856
	ds_read_b128 v[40:43], v136 offset:33856
	s_waitcnt lgkmcnt(5)
	v_mfma_f32_16x16x32_bf16 v[32:35], v[32:35], v[16:19], v[36:39]
	s_waitcnt lgkmcnt(4)
	v_mfma_f32_16x16x32_bf16 v[16:19], v[84:87], v[16:19], v[20:23]
	s_nop 2
	ds_read_b128 v[20:23], v115 offset:33920
	ds_read_b128 v[36:39], v136 offset:33920
	s_waitcnt lgkmcnt(5)
	v_mfma_f32_16x16x32_bf16 v[28:31], v[28:31], v[12:15], v[32:35]
	s_waitcnt lgkmcnt(4)
	v_mfma_f32_16x16x32_bf16 v[12:15], v[60:63], v[12:15], v[16:19]
	s_nop 2
	ds_read_b128 v[16:19], v115 offset:33984
	ds_read_b128 v[32:35], v136 offset:33984
	s_waitcnt lgkmcnt(5)
	v_mfma_f32_16x16x32_bf16 v[24:27], v[24:27], v[8:11], v[28:31]
	s_waitcnt lgkmcnt(4)
	v_mfma_f32_16x16x32_bf16 v[8:11], v[40:43], v[8:11], v[12:15]
	s_waitcnt lgkmcnt(3)
	v_mfma_f32_16x16x32_bf16 v[12:15], v[20:23], v[4:7], v[24:27]
	s_waitcnt lgkmcnt(2)
	v_mfma_f32_16x16x32_bf16 v[4:7], v[36:39], v[4:7], v[8:11]
	s_waitcnt lgkmcnt(1)
	v_mfma_f32_16x16x32_bf16 v[132:135], v[16:19], v[0:3], v[12:15]
	s_waitcnt lgkmcnt(0)
	v_mfma_f32_16x16x32_bf16 v[136:139], v[32:35], v[0:3], v[4:7]
	v_lshl_add_u64 v[0:1], s[0:1], 0, v[172:173]
	v_mad_u64_u32 v[2:3], s[10:11], v0, s69, v[180:181]
	v_mov_b32_e32 v0, v3
	v_mad_u64_u32 v[0:1], s[10:11], v1, s69, v[0:1]
	v_mov_b32_e32 v3, v0
	global_load_dwordx4 v[60:63], v[2:3], off
	global_load_dwordx4 v[12:15], v[2:3], off offset:2048
	v_lshl_add_u64 v[176:177], v[2:3], 0, v[170:171]
	global_load_dwordx4 v[40:43], v[176:177], off
	v_mov_b32_e32 v8, 0
	v_mov_b32_e32 v9, 0
	v_mov_b32_e32 v10, 0
	v_mov_b32_e32 v11, 0
	v_subrev_u32_e32 v232, 0x80, v199
	v_cmp_gt_u32_e64 s[100:101], 32, v232
	v_cmp_le_u32_e32 vcc, 0xc0, v199
	s_nop 0
	v_cndmask_b32_e64 v232, 0, 1, s[100:101]
	s_nop 0
	v_cndmask_b32_e64 v232, v232, 1, vcc
	v_cmp_ne_u32_e32 vcc, 0, v232
	s_mov_b64 exec, vcc
	global_load_dwordx4 v[8:11], v[176:177], off offset:2048
	s_mov_b64 exec, -1
	v_lshl_add_u64 v[176:177], v[176:177], 0, v[170:171]
	global_load_dwordx4 v[36:39], v[176:177], off
	v_mov_b32_e32 v4, 0
	v_mov_b32_e32 v5, 0
	v_mov_b32_e32 v6, 0
	v_mov_b32_e32 v7, 0
	v_subrev_u32_e32 v232, 0x100, v199
	v_cmp_gt_u32_e64 s[100:101], 32, v232
	v_cmp_le_u32_e32 vcc, 0x140, v199
	s_nop 0
	v_cndmask_b32_e64 v232, 0, 1, s[100:101]
	s_nop 0
	v_cndmask_b32_e64 v232, v232, 1, vcc
	v_cmp_ne_u32_e32 vcc, 0, v232
	s_mov_b64 exec, vcc
	global_load_dwordx4 v[4:7], v[176:177], off offset:2048
	s_mov_b64 exec, -1
	v_lshl_add_u64 v[176:177], v[176:177], 0, v[170:171]
	global_load_dwordx4 v[32:35], v[176:177], off
	v_mov_b32_e32 v0, 0
	v_mov_b32_e32 v1, 0
	v_mov_b32_e32 v2, 0
; __device__ __forceinline__ unsigned pk2(float lo, float hi) { const f32x2_t v = {lo, hi}; const bf16x2_t b = __builtin_convertvector(v, bf16x2_t); return __builtin_bit_cast(unsigned, b); }
; __global__ void __launch_bounds__(512, 2) fwd_megakernel(Params kp_) {
;     ...
;                                 { const size_t rown = (n < 63) ? row0 + 128 : row0; R2_LOAD_A(rown); }
; #pragma unroll
;                                 for (int ct = 0; ct < R2_NCT; ++ct) { bf16* op = (rep_ + 1 < REP_R2) ? (dmy + (wave * 16 + r16) * 64 + ct * 16 + g4 * 4) : (proj + (row0 + wave * 16 + r16) * RETP + 2048 + h * 512 + e0 + ct * 16 + g4 * 4);
;                                     u32x2 w; w.x = pk2(acc[ct][0], acc[ct][1]); w.y = pk2(acc[ct][2], acc[ct][3]); *(u32x2*)op = w; }
; #pragma unroll
;                                 for (int a = 0; a < R2_NCT; ++a) { Sacc[a][0] = Sacc[a][0] * gam; Sacc[a][1] = Sacc[a][1] * gam; }
;                                 {
;                                     bf16x8 vq[2][R2_NCT];
; #pragma unroll
;                                     for (int dt = 0; dt < R2_NCT; ++dt) vq[0][dt] = *(const bf16x8*)(VT + (dt * 16 + r16) * 136 + g4 * 8);
; #pragma unroll
;                                     for (int q = 0; q < 4; ++q) {
;                                         if (q + 1 < 4) {
; #pragma unroll
;                                             for (int dt = 0; dt < R2_NCT; ++dt) vq[(q + 1) & 1][dt] = *(const bf16x8*)(VT + (dt * 16 + r16) * 136 + (q + 1) * 32 + g4 * 8); }
;                                         __builtin_amdgcn_sched_barrier(0);
; #pragma unroll
;                                         for (int dt = 0; dt < R2_NCT; ++dt) { Sacc[dt][0] = MFMA16(vq[q & 1][dt], kfr[2 * q], Sacc[dt][0]); Sacc[dt][1] = MFMA16(vq[q & 1][dt], kfr[2 * q + 1], Sacc[dt][1]); }
;                                         __builtin_amdgcn_sched_barrier(0);
;                                     }
;                                 }
;                                 R2_LOAD_K(n < 63 ? n + 1 : n);
; #pragma unroll
;                                 for (int dt = 0; dt < R2_NCT; ++dt)
; #pragma unroll
;                                     for (int kt = 0; kt < 2; ++kt)
; #pragma unroll
;                                         for (int j = 0; j < 4; ++j) STn[(dt * 16 + g4 * 4 + j) * 264 + (2 * wave + kt) * 16 + r16] = (bf16)f2bf(Sacc[dt][kt][j]);
	v_mov_b32_e32 v3, 0
	v_subrev_u32_e32 v232, 0x180, v199
	v_cmp_gt_u32_e64 s[100:101], 32, v232
	v_cmp_le_u32_e32 vcc, 0x1c0, v199
	s_nop 0
	v_cndmask_b32_e64 v232, 0, 1, s[100:101]
	s_nop 0
	v_cndmask_b32_e64 v232, v232, 1, vcc
	v_cmp_ne_u32_e32 vcc, 0, v232
	s_mov_b64 exec, vcc
	global_load_dwordx4 v[0:3], v[176:177], off offset:2048
	s_mov_b64 exec, -1
	v_lshl_add_u64 v[176:177], v[176:177], 0, v[170:171]
	global_load_dwordx4 v[28:31], v[176:177], off
	v_lshl_add_u64 v[176:177], v[176:177], 0, v[170:171]
	global_load_dwordx4 v[24:27], v[176:177], off
	v_lshl_add_u64 v[176:177], v[176:177], 0, v[170:171]
	global_load_dwordx4 v[20:23], v[176:177], off
	v_lshl_add_u64 v[176:177], v[176:177], 0, v[170:171]
	global_load_dwordx4 v[16:19], v[176:177], off
	v_lshl_add_u64 v[84:85], s[0:1], 0, v[104:105]
	v_mov_b64_e32 v[86:87], s[52:53]
	v_mad_u64_u32 v[86:87], s[0:1], v84, s69, v[86:87]
	v_mov_b32_e32 v84, v87
	v_mad_u64_u32 v[84:85], s[0:1], v85, s69, v[84:85]
	v_mov_b32_e32 v87, v84
	v_lshl_add_u64 v[84:85], v[86:87], 0, s[94:95]
	v_lshl_add_u64 v[84:85], s[2:3], 1, v[84:85]
	v_lshl_add_u64 v[84:85], v[84:85], 0, v[112:113]
	v_add_co_u32_e64 v84, s[0:1], s64, v84
	v_cvt_pk_bf16_f32 v132, v132, v133
	s_nop 0
	v_addc_co_u32_e64 v85, s[0:1], 0, v85, s[0:1]
	global_load_dwordx4 v[84:87], v[84:85], off
	v_cvt_pk_bf16_f32 v133, v134, v135
	global_store_dwordx2 v[122:123], v[132:133], off offset:-32
	v_cvt_pk_bf16_f32 v132, v136, v137
	v_cvt_pk_bf16_f32 v133, v138, v139
	v_mov_b32_e32 v115, v114
	global_store_dwordx2 v[122:123], v[132:133], off
	v_pk_mul_f32 v[98:99], v[114:115], v[98:99]
	v_pk_mul_f32 v[94:95], v[114:115], v[94:95]
	v_pk_mul_f32 v[90:91], v[114:115], v[90:91]
	v_pk_mul_f32 v[82:83], v[114:115], v[82:83]
	v_add_u32_e32 v115, v131, v126
	ds_read_b128 v[132:135], v115 offset:33792
	ds_read_b128 v[136:139], v115 offset:38144
	ds_read_b128 v[140:143], v115 offset:33856
	ds_read_b128 v[144:147], v115 offset:38208
	v_pk_mul_f32 v[96:97], v[120:121], v[96:97]
	v_pk_mul_f32 v[92:93], v[120:121], v[92:93]
	v_pk_mul_f32 v[88:89], v[120:121], v[88:89]
	v_pk_mul_f32 v[80:81], v[120:121], v[80:81]
	s_waitcnt vmcnt(22) lgkmcnt(3)
	v_mfma_f32_16x16x32_bf16 v[96:99], v[132:135], v[52:55], v[96:99]
	s_waitcnt vmcnt(16)
	v_mfma_f32_16x16x32_bf16 v[92:95], v[132:135], v[76:79], v[92:95]
	s_waitcnt lgkmcnt(2)
	v_mfma_f32_16x16x32_bf16 v[52:55], v[136:139], v[52:55], v[88:91]
	v_mfma_f32_16x16x32_bf16 v[76:79], v[136:139], v[76:79], v[80:83]
	s_nop 2
	ds_read_b128 v[80:83], v115 offset:33920
	ds_read_b128 v[88:91], v115 offset:38272
	s_waitcnt vmcnt(20) lgkmcnt(3)
	v_mfma_f32_16x16x32_bf16 v[96:99], v[140:143], v[68:71], v[96:99]
	s_waitcnt vmcnt(18)
	v_mfma_f32_16x16x32_bf16 v[92:95], v[140:143], v[72:75], v[92:95]
	s_waitcnt lgkmcnt(2)
	v_mfma_f32_16x16x32_bf16 v[52:55], v[144:147], v[68:71], v[52:55]
	v_mfma_f32_16x16x32_bf16 v[68:71], v[144:147], v[72:75], v[76:79]
	ds_read_b128 v[72:75], v115 offset:33984
	s_nop 1
	ds_read_b128 v[76:79], v115 offset:38336
	s_waitcnt lgkmcnt(3)
	v_mfma_f32_16x16x32_bf16 v[96:99], v[80:83], v[48:51], v[96:99]
	s_waitcnt vmcnt(16)
	v_mfma_f32_16x16x32_bf16 v[80:83], v[80:83], v[64:67], v[92:95]
	s_waitcnt lgkmcnt(2)
	v_mfma_f32_16x16x32_bf16 v[48:51], v[88:91], v[48:51], v[52:55]
	v_mfma_f32_16x16x32_bf16 v[52:55], v[88:91], v[64:67], v[68:71]
	s_waitcnt lgkmcnt(1)
	v_mfma_f32_16x16x32_bf16 v[96:99], v[72:75], v[44:47], v[96:99]
	s_waitcnt vmcnt(15)
	v_mfma_f32_16x16x32_bf16 v[92:95], v[72:75], v[56:59], v[80:83]
	s_waitcnt lgkmcnt(0)
	v_mfma_f32_16x16x32_bf16 v[88:91], v[76:79], v[44:47], v[48:51]
	v_mfma_f32_16x16x32_bf16 v[80:83], v[76:79], v[56:59], v[52:55]
	s_mov_b32 s7, s95
	v_lshl_add_u64 v[44:45], s[6:7], 1, v[116:117]
	s_nop 0
	v_add_co_u32_e64 v58, s[0:1], s64, v44
	v_lshl_add_u64 v[56:57], v[44:45], 0, s[90:91]
	s_nop 0
	v_addc_co_u32_e64 v59, s[0:1], 0, v45, s[0:1]
	global_load_dwordx4 v[52:55], v[44:45], off
	global_load_dwordx4 v[68:71], v[44:45], off offset:1024
	global_load_dwordx4 v[72:75], v[56:57], off offset:1024
	global_load_dwordx4 v[64:67], v[56:57], off offset:2048
	global_load_dwordx4 v[48:51], v[44:45], off offset:2048
	s_nop 0
	global_load_dwordx4 v[44:47], v[44:45], off offset:3072
	s_nop 0
	global_load_dwordx4 v[76:79], v[58:59], off
	s_nop 0
	global_load_dwordx4 v[56:59], v[56:57], off offset:3072
	s_cselect_b32 s0, 0x4200, 0
	v_cvt_pk_bf16_f32 v115, v96, s0
	v_add_u32_e32 v131, s0, v128
	ds_write_b16 v131, v115
	v_cvt_pk_bf16_f32 v115, v97, s0
	ds_write_b16 v131, v115 offset:528
	v_cvt_pk_bf16_f32 v115, v98, s0
	ds_write_b16 v131, v115 offset:1056
	v_cvt_pk_bf16_f32 v115, v99, s0
	ds_write_b16 v131, v115 offset:1584
	v_cvt_pk_bf16_f32 v115, v92, s0
	ds_write_b16 v131, v115 offset:32
	v_cvt_pk_bf16_f32 v115, v93, s0
	ds_write_b16 v131, v115 offset:560
	v_cvt_pk_bf16_f32 v115, v94, s0
	ds_write_b16 v131, v115 offset:1088
	v_cvt_pk_bf16_f32 v115, v95, s0
	ds_write_b16 v131, v115 offset:1616
	v_cvt_pk_bf16_f32 v115, v88, s0
	ds_write_b16 v131, v115 offset:8448
	v_cvt_pk_bf16_f32 v115, v89, s0
	ds_write_b16 v131, v115 offset:8976
	v_cvt_pk_bf16_f32 v115, v90, s0
	ds_write_b16 v131, v115 offset:9504
	v_cvt_pk_bf16_f32 v115, v91, s0
	ds_write_b16 v131, v115 offset:10032
	v_cvt_pk_bf16_f32 v115, v80, s0
	ds_write_b16 v131, v115 offset:8480
	v_cvt_pk_bf16_f32 v115, v81, s0
	ds_write_b16 v131, v115 offset:9008
	v_cvt_pk_bf16_f32 v115, v82, s0
	ds_write_b16 v131, v115 offset:9536
	v_cvt_pk_bf16_f32 v115, v83, s0
	s_add_i32 s8, s8, 0x8000
	s_mov_b64 s[0:1], 0x184000
	v_lshl_add_u64 v[122:123], v[122:123], 0, s[0:1]
	s_cmp_eq_u32 s9, 64
	s_mov_b64 s[6:7], s[4:5]
	s_mov_b32 s0, s9
	ds_write_b16 v131, v115 offset:10064
	s_cbranch_scc0 .LBB0_558
	v_readlane_b32 s0, v254, 14
	s_add_i32 s17, s17, s88
	s_add_i32 s16, s16, s0
	s_cmpk_gt_i32 s17, 0xff
	s_cbranch_scc0 .LBB0_554
